# Nyquist-row DFT items (queue tail): all 32 row loads of an item in flight instead of 32 serialised load latencies
# baseline (speedup 1.0000x reference)
.LBB0_523:
	s_andn2_b64 vcc, exec, s[0:1]
	s_cbranch_vccnz .LBB0_314
	s_lshl_b32 s0, s53, 6
	v_add_u32_e32 v4, s0, v171
	v_lshlrev_b32_e32 v0, 2, v4
	v_and_b32_e32 v0, 0xfffff800, v0
	v_add_u32_e32 v2, 0x1000, v0
	v_add_u16_e32 v5, s0, v174
	v_ashrrev_i32_e32 v3, 31, v2
	v_lshlrev_b32_e32 v0, 1, v4
	v_and_b32_e32 v5, 0x7f, v5
	v_lshlrev_b64 v[2:3], 12, v[2:3]
	v_and_b32_e32 v0, 0x300, v0
	v_lshlrev_b32_e32 v5, 1, v5
	v_or3_b32 v2, v2, v0, v5
	v_readlane_b32 s0, v254, 40
	v_ashrrev_i32_e32 v5, 31, v4
	v_readlane_b32 s1, v254, 41
	v_lshlrev_b64 v[4:5], 13, v[4:5]
	v_lshl_add_u64 v[4:5], v[150:151], 0, v[4:5]
	v_lshl_add_u64 v[2:3], s[0:1], 0, v[2:3]
	s_mov_b64 s[4:5], 0x2000
	v_mov_b64_e32 v[10:11], v[4:5]
	global_load_dwordx4 v[16:19], v[10:11], off
	global_load_dwordx4 v[20:23], v[10:11], off offset:1024
	global_load_dwordx4 v[24:27], v[10:11], off offset:2048
	global_load_dwordx4 v[28:31], v[10:11], off offset:3072
	v_lshl_add_u64 v[10:11], v[10:11], 0, s[4:5]
	global_load_dwordx4 v[32:35], v[10:11], off
	global_load_dwordx4 v[36:39], v[10:11], off offset:1024
	global_load_dwordx4 v[40:43], v[10:11], off offset:2048
	global_load_dwordx4 v[44:47], v[10:11], off offset:3072
	v_lshl_add_u64 v[10:11], v[10:11], 0, s[4:5]
	global_load_dwordx4 v[48:51], v[10:11], off
	global_load_dwordx4 v[52:55], v[10:11], off offset:1024
	global_load_dwordx4 v[56:59], v[10:11], off offset:2048
	global_load_dwordx4 v[60:63], v[10:11], off offset:3072
	v_lshl_add_u64 v[10:11], v[10:11], 0, s[4:5]
	global_load_dwordx4 v[64:67], v[10:11], off
	global_load_dwordx4 v[68:71], v[10:11], off offset:1024
	global_load_dwordx4 v[72:75], v[10:11], off offset:2048
	global_load_dwordx4 v[76:79], v[10:11], off offset:3072
	v_lshl_add_u64 v[10:11], v[10:11], 0, s[4:5]
	global_load_dwordx4 v[80:83], v[10:11], off
	global_load_dwordx4 v[84:87], v[10:11], off offset:1024
	global_load_dwordx4 v[88:91], v[10:11], off offset:2048
	global_load_dwordx4 v[92:95], v[10:11], off offset:3072
	v_lshl_add_u64 v[10:11], v[10:11], 0, s[4:5]
	global_load_dwordx4 v[96:99], v[10:11], off
	global_load_dwordx4 v[100:103], v[10:11], off offset:1024
	global_load_dwordx4 v[104:107], v[10:11], off offset:2048
	global_load_dwordx4 v[108:111], v[10:11], off offset:3072
	v_lshl_add_u64 v[10:11], v[10:11], 0, s[4:5]
	global_load_dwordx4 v[112:115], v[10:11], off
	global_load_dwordx4 v[116:119], v[10:11], off offset:1024
	global_load_dwordx4 v[120:123], v[10:11], off offset:2048
	global_load_dwordx4 v[124:127], v[10:11], off offset:3072
	v_lshl_add_u64 v[10:11], v[10:11], 0, s[4:5]
	global_load_dwordx4 v[128:131], v[10:11], off
	global_load_dwordx4 v[132:135], v[10:11], off offset:1024
	global_load_dwordx4 v[136:139], v[10:11], off offset:2048
	global_load_dwordx4 v[140:143], v[10:11], off offset:3072
	s_waitcnt vmcnt(28)
	v_lshlrev_b32_e32 v0, 16, v16
	v_and_b32_e32 v7, 0xffff0000, v16
	v_sub_f32_e32 v0, v0, v7
	v_lshlrev_b32_e32 v7, 16, v17
	v_add_f32_e32 v0, v0, v7
	v_and_b32_e32 v7, 0xffff0000, v17
	v_sub_f32_e32 v0, v0, v7
	v_lshlrev_b32_e32 v7, 16, v18
	v_add_f32_e32 v0, v0, v7
	v_and_b32_e32 v7, 0xffff0000, v18
	v_sub_f32_e32 v0, v0, v7
	v_lshlrev_b32_e32 v7, 16, v19
	v_add_f32_e32 v0, v0, v7
	v_and_b32_e32 v7, 0xffff0000, v19
	v_sub_f32_e32 v0, v0, v7
	v_add_f32_e32 v0, 0, v0
	v_lshlrev_b32_e32 v6, 16, v20
	v_and_b32_e32 v7, 0xffff0000, v20
	v_sub_f32_e32 v6, v6, v7
	v_lshlrev_b32_e32 v7, 16, v21
	v_add_f32_e32 v6, v6, v7
	v_and_b32_e32 v7, 0xffff0000, v21
	v_sub_f32_e32 v6, v6, v7
	v_lshlrev_b32_e32 v7, 16, v22
	v_add_f32_e32 v6, v6, v7
	v_and_b32_e32 v7, 0xffff0000, v22
	v_sub_f32_e32 v6, v6, v7
	v_lshlrev_b32_e32 v7, 16, v23
	v_add_f32_e32 v6, v6, v7
	v_and_b32_e32 v7, 0xffff0000, v23
	v_sub_f32_e32 v6, v6, v7
	v_add_f32_e32 v0, v0, v6
	v_lshlrev_b32_e32 v6, 16, v24
	v_and_b32_e32 v7, 0xffff0000, v24
	v_sub_f32_e32 v6, v6, v7
	v_lshlrev_b32_e32 v7, 16, v25
	v_add_f32_e32 v6, v6, v7
	v_and_b32_e32 v7, 0xffff0000, v25
	v_sub_f32_e32 v6, v6, v7
	v_lshlrev_b32_e32 v7, 16, v26
	v_add_f32_e32 v6, v6, v7
	v_and_b32_e32 v7, 0xffff0000, v26
	v_sub_f32_e32 v6, v6, v7
	v_lshlrev_b32_e32 v7, 16, v27
	v_add_f32_e32 v6, v6, v7
	v_and_b32_e32 v7, 0xffff0000, v27
	v_sub_f32_e32 v6, v6, v7
	v_add_f32_e32 v0, v0, v6
	v_lshlrev_b32_e32 v6, 16, v28
	v_and_b32_e32 v7, 0xffff0000, v28
	v_sub_f32_e32 v6, v6, v7
	v_lshlrev_b32_e32 v7, 16, v29
	v_add_f32_e32 v6, v6, v7
	v_and_b32_e32 v7, 0xffff0000, v29
	v_sub_f32_e32 v6, v6, v7
	v_lshlrev_b32_e32 v7, 16, v30
	v_add_f32_e32 v6, v6, v7
	v_and_b32_e32 v7, 0xffff0000, v30
	v_sub_f32_e32 v6, v6, v7
	v_lshlrev_b32_e32 v7, 16, v31
	v_add_f32_e32 v6, v6, v7
	v_and_b32_e32 v7, 0xffff0000, v31
	v_sub_f32_e32 v6, v6, v7
	v_add_f32_e32 v0, v0, v6
	v_mov_b32_e32 v6, v1
	s_nop 0
	v_add_f32_dpp v0, v0, v0 quad_perm:[1,0,3,2] row_mask:0xf bank_mask:0xf bound_ctrl:1
	s_nop 1
	v_add_f32_dpp v0, v0, v0 quad_perm:[2,3,0,1] row_mask:0xf bank_mask:0xf bound_ctrl:1
	s_nop 1
	v_add_f32_dpp v0, v0, v0 row_half_mirror row_mask:0xf bank_mask:0xf bound_ctrl:1
	s_nop 1
	v_add_f32_dpp v0, v0, v0 row_mirror row_mask:0xf bank_mask:0xf bound_ctrl:1
	s_nop 1
	v_mov_b32_dpp v6, v0 row_bcast:15 row_mask:0xa bank_mask:0xf
	v_add_f32_e32 v0, v0, v6
	v_mov_b32_e32 v6, v1
	s_nop 1
	v_mov_b32_dpp v6, v0 row_bcast:31 row_mask:0xc bank_mask:0xf
	v_add_f32_e32 v0, v0, v6
	v_mov_b32_e32 v16, 0x3b000000
	v_readlane_b32 s8, v0, 63
	s_nop 3
	v_mul_f32_e32 v16, s8, v16
	v_cvt_pk_bf16_f32 v16, v16, v16
	s_waitcnt vmcnt(24)
	v_lshlrev_b32_e32 v0, 16, v32
	v_and_b32_e32 v7, 0xffff0000, v32
	v_sub_f32_e32 v0, v0, v7
	v_lshlrev_b32_e32 v7, 16, v33
	v_add_f32_e32 v0, v0, v7
	v_and_b32_e32 v7, 0xffff0000, v33
	v_sub_f32_e32 v0, v0, v7
	v_lshlrev_b32_e32 v7, 16, v34
	v_add_f32_e32 v0, v0, v7
	v_and_b32_e32 v7, 0xffff0000, v34
	v_sub_f32_e32 v0, v0, v7
	v_lshlrev_b32_e32 v7, 16, v35
	v_add_f32_e32 v0, v0, v7
	v_and_b32_e32 v7, 0xffff0000, v35
	v_sub_f32_e32 v0, v0, v7
	v_add_f32_e32 v0, 0, v0
	v_lshlrev_b32_e32 v6, 16, v36
	v_and_b32_e32 v7, 0xffff0000, v36
	v_sub_f32_e32 v6, v6, v7
	v_lshlrev_b32_e32 v7, 16, v37
	v_add_f32_e32 v6, v6, v7
	v_and_b32_e32 v7, 0xffff0000, v37
	v_sub_f32_e32 v6, v6, v7
	v_lshlrev_b32_e32 v7, 16, v38
	v_add_f32_e32 v6, v6, v7
	v_and_b32_e32 v7, 0xffff0000, v38
	v_sub_f32_e32 v6, v6, v7
	v_lshlrev_b32_e32 v7, 16, v39
	v_add_f32_e32 v6, v6, v7
	v_and_b32_e32 v7, 0xffff0000, v39
	v_sub_f32_e32 v6, v6, v7
	v_add_f32_e32 v0, v0, v6
	v_lshlrev_b32_e32 v6, 16, v40
	v_and_b32_e32 v7, 0xffff0000, v40
	v_sub_f32_e32 v6, v6, v7
	v_lshlrev_b32_e32 v7, 16, v41
	v_add_f32_e32 v6, v6, v7
	v_and_b32_e32 v7, 0xffff0000, v41
	v_sub_f32_e32 v6, v6, v7
	v_lshlrev_b32_e32 v7, 16, v42
	v_add_f32_e32 v6, v6, v7
	v_and_b32_e32 v7, 0xffff0000, v42
	v_sub_f32_e32 v6, v6, v7
	v_lshlrev_b32_e32 v7, 16, v43
	v_add_f32_e32 v6, v6, v7
	v_and_b32_e32 v7, 0xffff0000, v43
	v_sub_f32_e32 v6, v6, v7
	v_add_f32_e32 v0, v0, v6
	v_lshlrev_b32_e32 v6, 16, v44
	v_and_b32_e32 v7, 0xffff0000, v44
	v_sub_f32_e32 v6, v6, v7
	v_lshlrev_b32_e32 v7, 16, v45
	v_add_f32_e32 v6, v6, v7
	v_and_b32_e32 v7, 0xffff0000, v45
	v_sub_f32_e32 v6, v6, v7
	v_lshlrev_b32_e32 v7, 16, v46
	v_add_f32_e32 v6, v6, v7
	v_and_b32_e32 v7, 0xffff0000, v46
	v_sub_f32_e32 v6, v6, v7
	v_lshlrev_b32_e32 v7, 16, v47
	v_add_f32_e32 v6, v6, v7
	v_and_b32_e32 v7, 0xffff0000, v47
	v_sub_f32_e32 v6, v6, v7
	v_add_f32_e32 v0, v0, v6
	v_mov_b32_e32 v6, v1
	s_nop 0
	v_add_f32_dpp v0, v0, v0 quad_perm:[1,0,3,2] row_mask:0xf bank_mask:0xf bound_ctrl:1
	s_nop 1
	v_add_f32_dpp v0, v0, v0 quad_perm:[2,3,0,1] row_mask:0xf bank_mask:0xf bound_ctrl:1
	s_nop 1
	v_add_f32_dpp v0, v0, v0 row_half_mirror row_mask:0xf bank_mask:0xf bound_ctrl:1
	s_nop 1
	v_add_f32_dpp v0, v0, v0 row_mirror row_mask:0xf bank_mask:0xf bound_ctrl:1
	s_nop 1
	v_mov_b32_dpp v6, v0 row_bcast:15 row_mask:0xa bank_mask:0xf
	v_add_f32_e32 v0, v0, v6
	v_mov_b32_e32 v6, v1
	s_nop 1
	v_mov_b32_dpp v6, v0 row_bcast:31 row_mask:0xc bank_mask:0xf
	v_add_f32_e32 v0, v0, v6
	v_mov_b32_e32 v32, 0x3b000000
	v_readlane_b32 s8, v0, 63
	s_nop 3
	v_mul_f32_e32 v32, s8, v32
	v_cvt_pk_bf16_f32 v32, v32, v32
	s_waitcnt vmcnt(20)
	v_lshlrev_b32_e32 v0, 16, v48
	v_and_b32_e32 v7, 0xffff0000, v48
	v_sub_f32_e32 v0, v0, v7
	v_lshlrev_b32_e32 v7, 16, v49
	v_add_f32_e32 v0, v0, v7
	v_and_b32_e32 v7, 0xffff0000, v49
	v_sub_f32_e32 v0, v0, v7
	v_lshlrev_b32_e32 v7, 16, v50
	v_add_f32_e32 v0, v0, v7
	v_and_b32_e32 v7, 0xffff0000, v50
	v_sub_f32_e32 v0, v0, v7
	v_lshlrev_b32_e32 v7, 16, v51
	v_add_f32_e32 v0, v0, v7
	v_and_b32_e32 v7, 0xffff0000, v51
	v_sub_f32_e32 v0, v0, v7
	v_add_f32_e32 v0, 0, v0
	v_lshlrev_b32_e32 v6, 16, v52
	v_and_b32_e32 v7, 0xffff0000, v52
	v_sub_f32_e32 v6, v6, v7
	v_lshlrev_b32_e32 v7, 16, v53
	v_add_f32_e32 v6, v6, v7
	v_and_b32_e32 v7, 0xffff0000, v53
	v_sub_f32_e32 v6, v6, v7
	v_lshlrev_b32_e32 v7, 16, v54
	v_add_f32_e32 v6, v6, v7
	v_and_b32_e32 v7, 0xffff0000, v54
	v_sub_f32_e32 v6, v6, v7
	v_lshlrev_b32_e32 v7, 16, v55
	v_add_f32_e32 v6, v6, v7
	v_and_b32_e32 v7, 0xffff0000, v55
	v_sub_f32_e32 v6, v6, v7
	v_add_f32_e32 v0, v0, v6
	v_lshlrev_b32_e32 v6, 16, v56
	v_and_b32_e32 v7, 0xffff0000, v56
	v_sub_f32_e32 v6, v6, v7
	v_lshlrev_b32_e32 v7, 16, v57
	v_add_f32_e32 v6, v6, v7
	v_and_b32_e32 v7, 0xffff0000, v57
	v_sub_f32_e32 v6, v6, v7
	v_lshlrev_b32_e32 v7, 16, v58
	v_add_f32_e32 v6, v6, v7
	v_and_b32_e32 v7, 0xffff0000, v58
	v_sub_f32_e32 v6, v6, v7
	v_lshlrev_b32_e32 v7, 16, v59
	v_add_f32_e32 v6, v6, v7
	v_and_b32_e32 v7, 0xffff0000, v59
	v_sub_f32_e32 v6, v6, v7
	v_add_f32_e32 v0, v0, v6
	v_lshlrev_b32_e32 v6, 16, v60
	v_and_b32_e32 v7, 0xffff0000, v60
	v_sub_f32_e32 v6, v6, v7
	v_lshlrev_b32_e32 v7, 16, v61
	v_add_f32_e32 v6, v6, v7
	v_and_b32_e32 v7, 0xffff0000, v61
	v_sub_f32_e32 v6, v6, v7
	v_lshlrev_b32_e32 v7, 16, v62
	v_add_f32_e32 v6, v6, v7
	v_and_b32_e32 v7, 0xffff0000, v62
	v_sub_f32_e32 v6, v6, v7
	v_lshlrev_b32_e32 v7, 16, v63
	v_add_f32_e32 v6, v6, v7
	v_and_b32_e32 v7, 0xffff0000, v63
	v_sub_f32_e32 v6, v6, v7
	v_add_f32_e32 v0, v0, v6
	v_mov_b32_e32 v6, v1
	s_nop 0
	v_add_f32_dpp v0, v0, v0 quad_perm:[1,0,3,2] row_mask:0xf bank_mask:0xf bound_ctrl:1
	s_nop 1
	v_add_f32_dpp v0, v0, v0 quad_perm:[2,3,0,1] row_mask:0xf bank_mask:0xf bound_ctrl:1
	s_nop 1
	v_add_f32_dpp v0, v0, v0 row_half_mirror row_mask:0xf bank_mask:0xf bound_ctrl:1
	s_nop 1
	v_add_f32_dpp v0, v0, v0 row_mirror row_mask:0xf bank_mask:0xf bound_ctrl:1
	s_nop 1
	v_mov_b32_dpp v6, v0 row_bcast:15 row_mask:0xa bank_mask:0xf
	v_add_f32_e32 v0, v0, v6
	v_mov_b32_e32 v6, v1
	s_nop 1
	v_mov_b32_dpp v6, v0 row_bcast:31 row_mask:0xc bank_mask:0xf
	v_add_f32_e32 v0, v0, v6
	v_mov_b32_e32 v48, 0x3b000000
	v_readlane_b32 s8, v0, 63
	s_nop 3
	v_mul_f32_e32 v48, s8, v48
	v_cvt_pk_bf16_f32 v48, v48, v48
	s_waitcnt vmcnt(16)
	v_lshlrev_b32_e32 v0, 16, v64
	v_and_b32_e32 v7, 0xffff0000, v64
	v_sub_f32_e32 v0, v0, v7
	v_lshlrev_b32_e32 v7, 16, v65
	v_add_f32_e32 v0, v0, v7
	v_and_b32_e32 v7, 0xffff0000, v65
	v_sub_f32_e32 v0, v0, v7
	v_lshlrev_b32_e32 v7, 16, v66
	v_add_f32_e32 v0, v0, v7
	v_and_b32_e32 v7, 0xffff0000, v66
	v_sub_f32_e32 v0, v0, v7
	v_lshlrev_b32_e32 v7, 16, v67
	v_add_f32_e32 v0, v0, v7
	v_and_b32_e32 v7, 0xffff0000, v67
	v_sub_f32_e32 v0, v0, v7
	v_add_f32_e32 v0, 0, v0
	v_lshlrev_b32_e32 v6, 16, v68
	v_and_b32_e32 v7, 0xffff0000, v68
	v_sub_f32_e32 v6, v6, v7
	v_lshlrev_b32_e32 v7, 16, v69
	v_add_f32_e32 v6, v6, v7
	v_and_b32_e32 v7, 0xffff0000, v69
	v_sub_f32_e32 v6, v6, v7
	v_lshlrev_b32_e32 v7, 16, v70
	v_add_f32_e32 v6, v6, v7
	v_and_b32_e32 v7, 0xffff0000, v70
	v_sub_f32_e32 v6, v6, v7
	v_lshlrev_b32_e32 v7, 16, v71
	v_add_f32_e32 v6, v6, v7
	v_and_b32_e32 v7, 0xffff0000, v71
	v_sub_f32_e32 v6, v6, v7
	v_add_f32_e32 v0, v0, v6
	v_lshlrev_b32_e32 v6, 16, v72
	v_and_b32_e32 v7, 0xffff0000, v72
	v_sub_f32_e32 v6, v6, v7
	v_lshlrev_b32_e32 v7, 16, v73
	v_add_f32_e32 v6, v6, v7
	v_and_b32_e32 v7, 0xffff0000, v73
	v_sub_f32_e32 v6, v6, v7
	v_lshlrev_b32_e32 v7, 16, v74
	v_add_f32_e32 v6, v6, v7
	v_and_b32_e32 v7, 0xffff0000, v74
	v_sub_f32_e32 v6, v6, v7
	v_lshlrev_b32_e32 v7, 16, v75
	v_add_f32_e32 v6, v6, v7
	v_and_b32_e32 v7, 0xffff0000, v75
	v_sub_f32_e32 v6, v6, v7
	v_add_f32_e32 v0, v0, v6
	v_lshlrev_b32_e32 v6, 16, v76
	v_and_b32_e32 v7, 0xffff0000, v76
	v_sub_f32_e32 v6, v6, v7
	v_lshlrev_b32_e32 v7, 16, v77
	v_add_f32_e32 v6, v6, v7
	v_and_b32_e32 v7, 0xffff0000, v77
	v_sub_f32_e32 v6, v6, v7
	v_lshlrev_b32_e32 v7, 16, v78
	v_add_f32_e32 v6, v6, v7
	v_and_b32_e32 v7, 0xffff0000, v78
	v_sub_f32_e32 v6, v6, v7
	v_lshlrev_b32_e32 v7, 16, v79
	v_add_f32_e32 v6, v6, v7
	v_and_b32_e32 v7, 0xffff0000, v79
	v_sub_f32_e32 v6, v6, v7
	v_add_f32_e32 v0, v0, v6
	v_mov_b32_e32 v6, v1
	s_nop 0
	v_add_f32_dpp v0, v0, v0 quad_perm:[1,0,3,2] row_mask:0xf bank_mask:0xf bound_ctrl:1
	s_nop 1
	v_add_f32_dpp v0, v0, v0 quad_perm:[2,3,0,1] row_mask:0xf bank_mask:0xf bound_ctrl:1
	s_nop 1
	v_add_f32_dpp v0, v0, v0 row_half_mirror row_mask:0xf bank_mask:0xf bound_ctrl:1
	s_nop 1
	v_add_f32_dpp v0, v0, v0 row_mirror row_mask:0xf bank_mask:0xf bound_ctrl:1
	s_nop 1
	v_mov_b32_dpp v6, v0 row_bcast:15 row_mask:0xa bank_mask:0xf
	v_add_f32_e32 v0, v0, v6
	v_mov_b32_e32 v6, v1
	s_nop 1
	v_mov_b32_dpp v6, v0 row_bcast:31 row_mask:0xc bank_mask:0xf
	v_add_f32_e32 v0, v0, v6
	v_mov_b32_e32 v64, 0x3b000000
	v_readlane_b32 s8, v0, 63
	s_nop 3
	v_mul_f32_e32 v64, s8, v64
	v_cvt_pk_bf16_f32 v64, v64, v64
	s_waitcnt vmcnt(12)
	v_lshlrev_b32_e32 v0, 16, v80
	v_and_b32_e32 v7, 0xffff0000, v80
	v_sub_f32_e32 v0, v0, v7
	v_lshlrev_b32_e32 v7, 16, v81
	v_add_f32_e32 v0, v0, v7
	v_and_b32_e32 v7, 0xffff0000, v81
	v_sub_f32_e32 v0, v0, v7
	v_lshlrev_b32_e32 v7, 16, v82
	v_add_f32_e32 v0, v0, v7
	v_and_b32_e32 v7, 0xffff0000, v82
	v_sub_f32_e32 v0, v0, v7
	v_lshlrev_b32_e32 v7, 16, v83
	v_add_f32_e32 v0, v0, v7
	v_and_b32_e32 v7, 0xffff0000, v83
	v_sub_f32_e32 v0, v0, v7
	v_add_f32_e32 v0, 0, v0
	v_lshlrev_b32_e32 v6, 16, v84
	v_and_b32_e32 v7, 0xffff0000, v84
	v_sub_f32_e32 v6, v6, v7
	v_lshlrev_b32_e32 v7, 16, v85
	v_add_f32_e32 v6, v6, v7
	v_and_b32_e32 v7, 0xffff0000, v85
	v_sub_f32_e32 v6, v6, v7
	v_lshlrev_b32_e32 v7, 16, v86
	v_add_f32_e32 v6, v6, v7
	v_and_b32_e32 v7, 0xffff0000, v86
	v_sub_f32_e32 v6, v6, v7
	v_lshlrev_b32_e32 v7, 16, v87
	v_add_f32_e32 v6, v6, v7
	v_and_b32_e32 v7, 0xffff0000, v87
	v_sub_f32_e32 v6, v6, v7
	v_add_f32_e32 v0, v0, v6
	v_lshlrev_b32_e32 v6, 16, v88
	v_and_b32_e32 v7, 0xffff0000, v88
	v_sub_f32_e32 v6, v6, v7
	v_lshlrev_b32_e32 v7, 16, v89
	v_add_f32_e32 v6, v6, v7
	v_and_b32_e32 v7, 0xffff0000, v89
	v_sub_f32_e32 v6, v6, v7
	v_lshlrev_b32_e32 v7, 16, v90
	v_add_f32_e32 v6, v6, v7
	v_and_b32_e32 v7, 0xffff0000, v90
	v_sub_f32_e32 v6, v6, v7
	v_lshlrev_b32_e32 v7, 16, v91
	v_add_f32_e32 v6, v6, v7
	v_and_b32_e32 v7, 0xffff0000, v91
	v_sub_f32_e32 v6, v6, v7
	v_add_f32_e32 v0, v0, v6
	v_lshlrev_b32_e32 v6, 16, v92
	v_and_b32_e32 v7, 0xffff0000, v92
	v_sub_f32_e32 v6, v6, v7
	v_lshlrev_b32_e32 v7, 16, v93
	v_add_f32_e32 v6, v6, v7
	v_and_b32_e32 v7, 0xffff0000, v93
	v_sub_f32_e32 v6, v6, v7
	v_lshlrev_b32_e32 v7, 16, v94
	v_add_f32_e32 v6, v6, v7
	v_and_b32_e32 v7, 0xffff0000, v94
	v_sub_f32_e32 v6, v6, v7
	v_lshlrev_b32_e32 v7, 16, v95
	v_add_f32_e32 v6, v6, v7
	v_and_b32_e32 v7, 0xffff0000, v95
	v_sub_f32_e32 v6, v6, v7
	v_add_f32_e32 v0, v0, v6
	v_mov_b32_e32 v6, v1
	s_nop 0
	v_add_f32_dpp v0, v0, v0 quad_perm:[1,0,3,2] row_mask:0xf bank_mask:0xf bound_ctrl:1
	s_nop 1
	v_add_f32_dpp v0, v0, v0 quad_perm:[2,3,0,1] row_mask:0xf bank_mask:0xf bound_ctrl:1
	s_nop 1
	v_add_f32_dpp v0, v0, v0 row_half_mirror row_mask:0xf bank_mask:0xf bound_ctrl:1
	s_nop 1
	v_add_f32_dpp v0, v0, v0 row_mirror row_mask:0xf bank_mask:0xf bound_ctrl:1
	s_nop 1
	v_mov_b32_dpp v6, v0 row_bcast:15 row_mask:0xa bank_mask:0xf
	v_add_f32_e32 v0, v0, v6
	v_mov_b32_e32 v6, v1
	s_nop 1
	v_mov_b32_dpp v6, v0 row_bcast:31 row_mask:0xc bank_mask:0xf
	v_add_f32_e32 v0, v0, v6
	v_mov_b32_e32 v80, 0x3b000000
	v_readlane_b32 s8, v0, 63
	s_nop 3
	v_mul_f32_e32 v80, s8, v80
	v_cvt_pk_bf16_f32 v80, v80, v80
	s_waitcnt vmcnt(8)
	v_lshlrev_b32_e32 v0, 16, v96
	v_and_b32_e32 v7, 0xffff0000, v96
	v_sub_f32_e32 v0, v0, v7
	v_lshlrev_b32_e32 v7, 16, v97
	v_add_f32_e32 v0, v0, v7
	v_and_b32_e32 v7, 0xffff0000, v97
	v_sub_f32_e32 v0, v0, v7
	v_lshlrev_b32_e32 v7, 16, v98
	v_add_f32_e32 v0, v0, v7
	v_and_b32_e32 v7, 0xffff0000, v98
	v_sub_f32_e32 v0, v0, v7
	v_lshlrev_b32_e32 v7, 16, v99
	v_add_f32_e32 v0, v0, v7
	v_and_b32_e32 v7, 0xffff0000, v99
	v_sub_f32_e32 v0, v0, v7
	v_add_f32_e32 v0, 0, v0
	v_lshlrev_b32_e32 v6, 16, v100
	v_and_b32_e32 v7, 0xffff0000, v100
	v_sub_f32_e32 v6, v6, v7
	v_lshlrev_b32_e32 v7, 16, v101
	v_add_f32_e32 v6, v6, v7
	v_and_b32_e32 v7, 0xffff0000, v101
	v_sub_f32_e32 v6, v6, v7
	v_lshlrev_b32_e32 v7, 16, v102
	v_add_f32_e32 v6, v6, v7
	v_and_b32_e32 v7, 0xffff0000, v102
	v_sub_f32_e32 v6, v6, v7
	v_lshlrev_b32_e32 v7, 16, v103
	v_add_f32_e32 v6, v6, v7
	v_and_b32_e32 v7, 0xffff0000, v103
	v_sub_f32_e32 v6, v6, v7
	v_add_f32_e32 v0, v0, v6
	v_lshlrev_b32_e32 v6, 16, v104
	v_and_b32_e32 v7, 0xffff0000, v104
	v_sub_f32_e32 v6, v6, v7
	v_lshlrev_b32_e32 v7, 16, v105
	v_add_f32_e32 v6, v6, v7
	v_and_b32_e32 v7, 0xffff0000, v105
	v_sub_f32_e32 v6, v6, v7
	v_lshlrev_b32_e32 v7, 16, v106
	v_add_f32_e32 v6, v6, v7
	v_and_b32_e32 v7, 0xffff0000, v106
	v_sub_f32_e32 v6, v6, v7
	v_lshlrev_b32_e32 v7, 16, v107
	v_add_f32_e32 v6, v6, v7
	v_and_b32_e32 v7, 0xffff0000, v107
	v_sub_f32_e32 v6, v6, v7
	v_add_f32_e32 v0, v0, v6
	v_lshlrev_b32_e32 v6, 16, v108
	v_and_b32_e32 v7, 0xffff0000, v108
	v_sub_f32_e32 v6, v6, v7
	v_lshlrev_b32_e32 v7, 16, v109
	v_add_f32_e32 v6, v6, v7
	v_and_b32_e32 v7, 0xffff0000, v109
	v_sub_f32_e32 v6, v6, v7
	v_lshlrev_b32_e32 v7, 16, v110
	v_add_f32_e32 v6, v6, v7
	v_and_b32_e32 v7, 0xffff0000, v110
	v_sub_f32_e32 v6, v6, v7
	v_lshlrev_b32_e32 v7, 16, v111
	v_add_f32_e32 v6, v6, v7
	v_and_b32_e32 v7, 0xffff0000, v111
	v_sub_f32_e32 v6, v6, v7
	v_add_f32_e32 v0, v0, v6
	v_mov_b32_e32 v6, v1
	s_nop 0
	v_add_f32_dpp v0, v0, v0 quad_perm:[1,0,3,2] row_mask:0xf bank_mask:0xf bound_ctrl:1
	s_nop 1
	v_add_f32_dpp v0, v0, v0 quad_perm:[2,3,0,1] row_mask:0xf bank_mask:0xf bound_ctrl:1
	s_nop 1
	v_add_f32_dpp v0, v0, v0 row_half_mirror row_mask:0xf bank_mask:0xf bound_ctrl:1
	s_nop 1
	v_add_f32_dpp v0, v0, v0 row_mirror row_mask:0xf bank_mask:0xf bound_ctrl:1
	s_nop 1
	v_mov_b32_dpp v6, v0 row_bcast:15 row_mask:0xa bank_mask:0xf
	v_add_f32_e32 v0, v0, v6
	v_mov_b32_e32 v6, v1
	s_nop 1
	v_mov_b32_dpp v6, v0 row_bcast:31 row_mask:0xc bank_mask:0xf
	v_add_f32_e32 v0, v0, v6
	v_mov_b32_e32 v96, 0x3b000000
	v_readlane_b32 s8, v0, 63
	s_nop 3
	v_mul_f32_e32 v96, s8, v96
	v_cvt_pk_bf16_f32 v96, v96, v96
	s_waitcnt vmcnt(4)
	v_lshlrev_b32_e32 v0, 16, v112
	v_and_b32_e32 v7, 0xffff0000, v112
	v_sub_f32_e32 v0, v0, v7
	v_lshlrev_b32_e32 v7, 16, v113
	v_add_f32_e32 v0, v0, v7
	v_and_b32_e32 v7, 0xffff0000, v113
	v_sub_f32_e32 v0, v0, v7
	v_lshlrev_b32_e32 v7, 16, v114
	v_add_f32_e32 v0, v0, v7
	v_and_b32_e32 v7, 0xffff0000, v114
	v_sub_f32_e32 v0, v0, v7
	v_lshlrev_b32_e32 v7, 16, v115
	v_add_f32_e32 v0, v0, v7
	v_and_b32_e32 v7, 0xffff0000, v115
	v_sub_f32_e32 v0, v0, v7
	v_add_f32_e32 v0, 0, v0
	v_lshlrev_b32_e32 v6, 16, v116
	v_and_b32_e32 v7, 0xffff0000, v116
	v_sub_f32_e32 v6, v6, v7
	v_lshlrev_b32_e32 v7, 16, v117
	v_add_f32_e32 v6, v6, v7
	v_and_b32_e32 v7, 0xffff0000, v117
	v_sub_f32_e32 v6, v6, v7
	v_lshlrev_b32_e32 v7, 16, v118
	v_add_f32_e32 v6, v6, v7
	v_and_b32_e32 v7, 0xffff0000, v118
	v_sub_f32_e32 v6, v6, v7
	v_lshlrev_b32_e32 v7, 16, v119
	v_add_f32_e32 v6, v6, v7
	v_and_b32_e32 v7, 0xffff0000, v119
	v_sub_f32_e32 v6, v6, v7
	v_add_f32_e32 v0, v0, v6
	v_lshlrev_b32_e32 v6, 16, v120
	v_and_b32_e32 v7, 0xffff0000, v120
	v_sub_f32_e32 v6, v6, v7
	v_lshlrev_b32_e32 v7, 16, v121
	v_add_f32_e32 v6, v6, v7
	v_and_b32_e32 v7, 0xffff0000, v121
	v_sub_f32_e32 v6, v6, v7
	v_lshlrev_b32_e32 v7, 16, v122
	v_add_f32_e32 v6, v6, v7
	v_and_b32_e32 v7, 0xffff0000, v122
	v_sub_f32_e32 v6, v6, v7
	v_lshlrev_b32_e32 v7, 16, v123
	v_add_f32_e32 v6, v6, v7
	v_and_b32_e32 v7, 0xffff0000, v123
	v_sub_f32_e32 v6, v6, v7
	v_add_f32_e32 v0, v0, v6
	v_lshlrev_b32_e32 v6, 16, v124
	v_and_b32_e32 v7, 0xffff0000, v124
	v_sub_f32_e32 v6, v6, v7
	v_lshlrev_b32_e32 v7, 16, v125
	v_add_f32_e32 v6, v6, v7
	v_and_b32_e32 v7, 0xffff0000, v125
	v_sub_f32_e32 v6, v6, v7
	v_lshlrev_b32_e32 v7, 16, v126
	v_add_f32_e32 v6, v6, v7
	v_and_b32_e32 v7, 0xffff0000, v126
	v_sub_f32_e32 v6, v6, v7
	v_lshlrev_b32_e32 v7, 16, v127
	v_add_f32_e32 v6, v6, v7
	v_and_b32_e32 v7, 0xffff0000, v127
	v_sub_f32_e32 v6, v6, v7
	v_add_f32_e32 v0, v0, v6
	v_mov_b32_e32 v6, v1
	s_nop 0
	v_add_f32_dpp v0, v0, v0 quad_perm:[1,0,3,2] row_mask:0xf bank_mask:0xf bound_ctrl:1
	s_nop 1
	v_add_f32_dpp v0, v0, v0 quad_perm:[2,3,0,1] row_mask:0xf bank_mask:0xf bound_ctrl:1
	s_nop 1
	v_add_f32_dpp v0, v0, v0 row_half_mirror row_mask:0xf bank_mask:0xf bound_ctrl:1
	s_nop 1
	v_add_f32_dpp v0, v0, v0 row_mirror row_mask:0xf bank_mask:0xf bound_ctrl:1
	s_nop 1
	v_mov_b32_dpp v6, v0 row_bcast:15 row_mask:0xa bank_mask:0xf
	v_add_f32_e32 v0, v0, v6
	v_mov_b32_e32 v6, v1
	s_nop 1
	v_mov_b32_dpp v6, v0 row_bcast:31 row_mask:0xc bank_mask:0xf
	v_add_f32_e32 v0, v0, v6
	v_mov_b32_e32 v112, 0x3b000000
	v_readlane_b32 s8, v0, 63
	s_nop 3
	v_mul_f32_e32 v112, s8, v112
	v_cvt_pk_bf16_f32 v112, v112, v112
	s_waitcnt vmcnt(0)
	v_lshlrev_b32_e32 v0, 16, v128
	v_and_b32_e32 v7, 0xffff0000, v128
	v_sub_f32_e32 v0, v0, v7
	v_lshlrev_b32_e32 v7, 16, v129
	v_add_f32_e32 v0, v0, v7
	v_and_b32_e32 v7, 0xffff0000, v129
	v_sub_f32_e32 v0, v0, v7
	v_lshlrev_b32_e32 v7, 16, v130
	v_add_f32_e32 v0, v0, v7
	v_and_b32_e32 v7, 0xffff0000, v130
	v_sub_f32_e32 v0, v0, v7
	v_lshlrev_b32_e32 v7, 16, v131
	v_add_f32_e32 v0, v0, v7
	v_and_b32_e32 v7, 0xffff0000, v131
	v_sub_f32_e32 v0, v0, v7
	v_add_f32_e32 v0, 0, v0
	v_lshlrev_b32_e32 v6, 16, v132
	v_and_b32_e32 v7, 0xffff0000, v132
	v_sub_f32_e32 v6, v6, v7
	v_lshlrev_b32_e32 v7, 16, v133
	v_add_f32_e32 v6, v6, v7
	v_and_b32_e32 v7, 0xffff0000, v133
	v_sub_f32_e32 v6, v6, v7
	v_lshlrev_b32_e32 v7, 16, v134
	v_add_f32_e32 v6, v6, v7
	v_and_b32_e32 v7, 0xffff0000, v134
	v_sub_f32_e32 v6, v6, v7
	v_lshlrev_b32_e32 v7, 16, v135
	v_add_f32_e32 v6, v6, v7
	v_and_b32_e32 v7, 0xffff0000, v135
	v_sub_f32_e32 v6, v6, v7
	v_add_f32_e32 v0, v0, v6
	v_lshlrev_b32_e32 v6, 16, v136
	v_and_b32_e32 v7, 0xffff0000, v136
	v_sub_f32_e32 v6, v6, v7
	v_lshlrev_b32_e32 v7, 16, v137
	v_add_f32_e32 v6, v6, v7
	v_and_b32_e32 v7, 0xffff0000, v137
	v_sub_f32_e32 v6, v6, v7
	v_lshlrev_b32_e32 v7, 16, v138
	v_add_f32_e32 v6, v6, v7
	v_and_b32_e32 v7, 0xffff0000, v138
	v_sub_f32_e32 v6, v6, v7
	v_lshlrev_b32_e32 v7, 16, v139
	v_add_f32_e32 v6, v6, v7
	v_and_b32_e32 v7, 0xffff0000, v139
	v_sub_f32_e32 v6, v6, v7
	v_add_f32_e32 v0, v0, v6
	v_lshlrev_b32_e32 v6, 16, v140
	v_and_b32_e32 v7, 0xffff0000, v140
	v_sub_f32_e32 v6, v6, v7
	v_lshlrev_b32_e32 v7, 16, v141
	v_add_f32_e32 v6, v6, v7
	v_and_b32_e32 v7, 0xffff0000, v141
	v_sub_f32_e32 v6, v6, v7
	v_lshlrev_b32_e32 v7, 16, v142
	v_add_f32_e32 v6, v6, v7
	v_and_b32_e32 v7, 0xffff0000, v142
	v_sub_f32_e32 v6, v6, v7
	v_lshlrev_b32_e32 v7, 16, v143
	v_add_f32_e32 v6, v6, v7
	v_and_b32_e32 v7, 0xffff0000, v143
	v_sub_f32_e32 v6, v6, v7
	v_add_f32_e32 v0, v0, v6
	v_mov_b32_e32 v6, v1
	s_nop 0
	v_add_f32_dpp v0, v0, v0 quad_perm:[1,0,3,2] row_mask:0xf bank_mask:0xf bound_ctrl:1
	s_nop 1
	v_add_f32_dpp v0, v0, v0 quad_perm:[2,3,0,1] row_mask:0xf bank_mask:0xf bound_ctrl:1
	s_nop 1
	v_add_f32_dpp v0, v0, v0 row_half_mirror row_mask:0xf bank_mask:0xf bound_ctrl:1
	s_nop 1
	v_add_f32_dpp v0, v0, v0 row_mirror row_mask:0xf bank_mask:0xf bound_ctrl:1
	s_nop 1
	v_mov_b32_dpp v6, v0 row_bcast:15 row_mask:0xa bank_mask:0xf
	v_add_f32_e32 v0, v0, v6
	v_mov_b32_e32 v6, v1
	s_nop 1
	v_mov_b32_dpp v6, v0 row_bcast:31 row_mask:0xc bank_mask:0xf
	v_add_f32_e32 v0, v0, v6
	v_mov_b32_e32 v128, 0x3b000000
	v_readlane_b32 s8, v0, 63
	s_nop 3
	v_mul_f32_e32 v128, s8, v128
	v_cvt_pk_bf16_f32 v128, v128, v128
	s_and_saveexec_b64 s[0:1], s[6:7]
	global_store_short v[2:3], v16, off
	global_store_short v[2:3], v32, off offset:2
	global_store_short v[2:3], v48, off offset:4
	global_store_short v[2:3], v64, off offset:6
	global_store_short v[2:3], v80, off offset:8
	global_store_short v[2:3], v96, off offset:10
	global_store_short v[2:3], v112, off offset:12
	global_store_short v[2:3], v128, off offset:14
	s_or_b64 exec, exec, s[0:1]
	s_branch .LBB0_314
